# P0 weight-fold GEMM: per-segment setprio flips removed too (no s_setprio left in the kernel)
# baseline (speedup 1.0000x reference)
.LBB0_14:
	s_and_b32 s35, s13, 3
	s_lshl_b32 s13, s20, 13
	s_lshl_b32 s21, s35, 12
	s_add_u32 s0, s10, 0x20080
	s_addc_u32 s1, s11, 0
	s_add_i32 s36, 0, 0x18000
	s_add_i32 s39, s36, s12
	v_lshl_add_u64 v[2:3], s[0:1], 0, v[66:67]
	s_mov_b32 m0, s39
	v_lshl_add_u64 v[6:7], s[0:1], 0, v[34:35]
	s_add_i32 s45, s39, 0x2000
	s_mov_b64 s[0:1], 0x80
	s_add_i32 s44, s53, 0x8000
	s_add_i32 s48, s53, 0xa000
	s_waitcnt vmcnt(2)
	s_barrier
	global_load_lds_dwordx4 v[2:3], off
	s_mov_b32 m0, s45
	v_lshl_add_u64 v[4:5], v[22:23], 0, s[0:1]
	v_lshl_add_u64 v[8:9], v[24:25], 0, s[0:1]
	s_add_u32 s0, s10, 0x24080
	global_load_lds_dwordx4 v[6:7], off
	s_mov_b32 m0, s44
	s_addc_u32 s1, s11, 0
	s_add_i32 s37, 0, 0x1c000
	global_load_lds_dwordx4 v[4:5], off
	s_mov_b32 m0, s48
	s_add_i32 s51, s37, s12
	global_load_lds_dwordx4 v[8:9], off
	v_lshl_add_u64 v[10:11], s[0:1], 0, v[66:67]
	s_mov_b32 m0, s51
	s_add_i32 s52, s51, 0x2000
	global_load_lds_dwordx4 v[10:11], off
	v_lshl_add_u64 v[12:13], s[0:1], 0, v[34:35]
	s_mov_b32 m0, s52
	v_lshrrev_b32_e32 v38, 1, v36
	global_load_lds_dwordx4 v[12:13], off
	v_and_b32_e32 v38, 24, v38
	s_add_i32 s56, 0, 0x10000
	s_add_i32 s58, 0, 0x14000
	v_and_b32_e32 v37, 15, v36
	v_lshlrev_b32_e32 v131, 1, v38
	v_lshlrev_b32_e32 v36, 2, v36
	s_add_u32 s40, s10, 0x20100
	v_lshl_or_b32 v132, s20, 6, v37
	v_lshl_or_b32 v37, v37, 6, v131
	v_and_b32_e32 v36, 32, v36
	s_addc_u32 s41, s11, 0
	v_bitop3_b32 v38, v37, s13, v36 bitop3:0xde
	v_bitop3_b32 v36, v37, s21, v36 bitop3:0xde
	s_add_u32 s62, s10, 0x10080
	v_add_u32_e32 v128, s56, v36
	s_addc_u32 s63, s11, 0
	s_add_i32 s56, s56, s12
	s_add_i32 s60, s53, 0xc000
	s_add_i32 s59, s53, 0xe000
	s_add_i32 s55, s56, 0x2000
	s_waitcnt vmcnt(6)
	s_barrier
	v_add_u32_e32 v129, s58, v36
	v_add_u32_e32 v133, 0, v38
	v_add_u32_e32 v242, s36, v36
	v_add_u32_e32 v243, s37, v36
	s_add_u32 s46, s10, 0x24100
	ds_read_b128 v[36:39], v128
	ds_read_b128 v[40:43], v128 offset:1024
	ds_read_b128 v[44:47], v128 offset:2048
	ds_read_b128 v[48:51], v128 offset:3072
	ds_read_b128 v[52:55], v129
	ds_read_b128 v[56:59], v129 offset:1024
	ds_read_b128 v[60:63], v129 offset:2048
	ds_read_b128 v[68:71], v129 offset:3072
	s_addc_u32 s47, s11, 0
	s_add_i32 s58, s58, s12
	s_add_i32 s57, s58, 0x2000
	s_add_u32 s12, s10, 0x10100
	s_addc_u32 s13, s11, 0
	s_add_u32 s36, s10, 0x20180
	s_addc_u32 s37, s11, 0
	s_add_u32 s20, s10, 0x24180
	s_addc_u32 s21, s11, 0
	s_add_u32 s0, s10, 0x10180
	s_addc_u32 s1, s11, 0
	s_cmpk_gt_u32 s61, 0xff
	s_mov_b32 m0, s60
	v_lshl_add_u64 v[64:65], s[62:63], 0, v[18:19]
	ds_read_b128 v[72:75], v133
	ds_read_b128 v[76:79], v133 offset:1024
	ds_read_b128 v[80:83], v133 offset:2048
	ds_read_b128 v[84:87], v133 offset:3072
	ds_read_b128 v[88:91], v133 offset:4096
	ds_read_b128 v[92:95], v133 offset:5120
	ds_read_b128 v[96:99], v133 offset:6144
	ds_read_b128 v[100:103], v133 offset:7168
	global_load_lds_dwordx4 v[64:65], off
	v_lshl_add_u64 v[64:65], s[62:63], 0, v[32:33]
	s_mov_b32 m0, s59
	s_nop 0
	global_load_lds_dwordx4 v[64:65], off
	s_waitcnt vmcnt(8)
	s_waitcnt lgkmcnt(0)
	s_barrier
	s_waitcnt lgkmcnt(0)
	v_mfma_f32_16x16x32_bf16 v[104:107], v[36:39], v[72:75], 0
	v_mfma_f32_16x16x32_bf16 v[108:111], v[44:47], v[72:75], 0
	v_mfma_f32_16x16x32_bf16 v[112:115], v[36:39], v[80:83], 0
	v_mfma_f32_16x16x32_bf16 v[116:119], v[44:47], v[80:83], 0
	v_mfma_f32_16x16x32_bf16 v[120:123], v[36:39], v[88:91], 0
	v_mfma_f32_16x16x32_bf16 v[124:127], v[44:47], v[88:91], 0
	v_mfma_f32_16x16x32_bf16 v[104:107], v[40:43], v[76:79], v[104:107]
	v_mfma_f32_16x16x32_bf16 v[108:111], v[48:51], v[76:79], v[108:111]
	v_mfma_f32_16x16x32_bf16 v[112:115], v[40:43], v[84:87], v[112:115]
	v_mfma_f32_16x16x32_bf16 v[116:119], v[48:51], v[84:87], v[116:119]
	v_mfma_f32_16x16x32_bf16 v[120:123], v[40:43], v[92:95], v[120:123]
	v_mfma_f32_16x16x32_bf16 v[124:127], v[48:51], v[92:95], v[124:127]
	v_mfma_f32_16x16x32_bf16 v[134:137], v[36:39], v[96:99], 0
	v_mfma_f32_16x16x32_bf16 v[138:141], v[44:47], v[96:99], 0
	v_mfma_f32_16x16x32_bf16 v[134:137], v[40:43], v[100:103], v[134:137]
	v_mfma_f32_16x16x32_bf16 v[138:141], v[48:51], v[100:103], v[138:141]
	v_mfma_f32_16x16x32_bf16 v[142:145], v[52:55], v[72:75], 0
	v_mfma_f32_16x16x32_bf16 v[72:75], v[60:63], v[72:75], 0
	v_mfma_f32_16x16x32_bf16 v[142:145], v[56:59], v[76:79], v[142:145]
	v_mfma_f32_16x16x32_bf16 v[72:75], v[68:71], v[76:79], v[72:75]
	v_mfma_f32_16x16x32_bf16 v[76:79], v[52:55], v[80:83], 0
	v_mfma_f32_16x16x32_bf16 v[80:83], v[60:63], v[80:83], 0
	v_mfma_f32_16x16x32_bf16 v[76:79], v[56:59], v[84:87], v[76:79]
	v_mfma_f32_16x16x32_bf16 v[80:83], v[68:71], v[84:87], v[80:83]
	v_mfma_f32_16x16x32_bf16 v[84:87], v[52:55], v[88:91], 0
	v_mfma_f32_16x16x32_bf16 v[88:91], v[60:63], v[88:91], 0
	v_mfma_f32_16x16x32_bf16 v[84:87], v[56:59], v[92:95], v[84:87]
	v_mfma_f32_16x16x32_bf16 v[88:91], v[68:71], v[92:95], v[88:91]
	v_mfma_f32_16x16x32_bf16 v[92:95], v[52:55], v[96:99], 0
	v_mfma_f32_16x16x32_bf16 v[96:99], v[60:63], v[96:99], 0
	v_mfma_f32_16x16x32_bf16 v[92:95], v[56:59], v[100:103], v[92:95]
	v_mfma_f32_16x16x32_bf16 v[96:99], v[68:71], v[100:103], v[96:99]
	s_barrier
	s_mov_b32 m0, s56
	v_lshl_add_u64 v[64:65], s[40:41], 0, v[66:67]
	ds_read_b128 v[100:103], v133 offset:16384
	ds_read_b128 v[146:149], v133 offset:17408
	ds_read_b128 v[150:153], v133 offset:18432
	ds_read_b128 v[154:157], v133 offset:19456
	ds_read_b128 v[158:161], v133 offset:20480
	ds_read_b128 v[162:165], v133 offset:21504
	ds_read_b128 v[166:169], v133 offset:22528
	ds_read_b128 v[170:173], v133 offset:23552
	global_load_lds_dwordx4 v[64:65], off
	v_lshl_add_u64 v[64:65], s[40:41], 0, v[34:35]
	s_mov_b32 m0, s55
	s_mov_b64 s[10:11], 0x100
	global_load_lds_dwordx4 v[64:65], off
	v_lshl_add_u64 v[64:65], s[46:47], 0, v[66:67]
	s_mov_b32 m0, s58
	s_nop 0
	global_load_lds_dwordx4 v[64:65], off
	v_lshl_add_u64 v[64:65], s[46:47], 0, v[34:35]
	s_mov_b32 m0, s57
	s_nop 0
	global_load_lds_dwordx4 v[64:65], off
	v_lshl_add_u64 v[64:65], v[22:23], 0, s[10:11]
	s_mov_b32 m0, s53
	s_nop 0
	global_load_lds_dwordx4 v[64:65], off
	v_lshl_add_u64 v[64:65], v[24:25], 0, s[10:11]
	s_mov_b32 m0, s54
	s_nop 0
	global_load_lds_dwordx4 v[64:65], off
	s_waitcnt vmcnt(8)
	s_waitcnt lgkmcnt(0)
	s_barrier
	s_waitcnt lgkmcnt(0)
	v_mfma_f32_16x16x32_bf16 v[174:177], v[36:39], v[100:103], 0
	v_mfma_f32_16x16x32_bf16 v[182:185], v[36:39], v[150:153], 0
	v_mfma_f32_16x16x32_bf16 v[190:193], v[36:39], v[158:161], 0
	v_mfma_f32_16x16x32_bf16 v[36:39], v[36:39], v[166:169], 0
	v_mfma_f32_16x16x32_bf16 v[174:177], v[40:43], v[146:149], v[174:177]
	v_mfma_f32_16x16x32_bf16 v[182:185], v[40:43], v[154:157], v[182:185]
	v_mfma_f32_16x16x32_bf16 v[190:193], v[40:43], v[162:165], v[190:193]
	v_mfma_f32_16x16x32_bf16 v[36:39], v[40:43], v[170:173], v[36:39]
	v_mfma_f32_16x16x32_bf16 v[40:43], v[44:47], v[166:169], 0
	v_mfma_f32_16x16x32_bf16 v[178:181], v[44:47], v[100:103], 0
	v_mfma_f32_16x16x32_bf16 v[186:189], v[44:47], v[150:153], 0
	v_mfma_f32_16x16x32_bf16 v[194:197], v[44:47], v[158:161], 0
	v_mfma_f32_16x16x32_bf16 v[40:43], v[48:51], v[170:173], v[40:43]
	v_mfma_f32_16x16x32_bf16 v[178:181], v[48:51], v[146:149], v[178:181]
	v_mfma_f32_16x16x32_bf16 v[186:189], v[48:51], v[154:157], v[186:189]
	v_mfma_f32_16x16x32_bf16 v[194:197], v[48:51], v[162:165], v[194:197]
	v_mfma_f32_16x16x32_bf16 v[44:47], v[52:55], v[100:103], 0
	v_mfma_f32_16x16x32_bf16 v[48:51], v[60:63], v[100:103], 0
	v_mfma_f32_16x16x32_bf16 v[44:47], v[56:59], v[146:149], v[44:47]
	v_mfma_f32_16x16x32_bf16 v[48:51], v[68:71], v[146:149], v[48:51]
	v_mfma_f32_16x16x32_bf16 v[100:103], v[52:55], v[150:153], 0
	v_mfma_f32_16x16x32_bf16 v[146:149], v[60:63], v[150:153], 0
	v_mfma_f32_16x16x32_bf16 v[150:153], v[52:55], v[158:161], 0
	v_mfma_f32_16x16x32_bf16 v[52:55], v[52:55], v[166:169], 0
	v_mfma_f32_16x16x32_bf16 v[100:103], v[56:59], v[154:157], v[100:103]
	v_mfma_f32_16x16x32_bf16 v[150:153], v[56:59], v[162:165], v[150:153]
	v_mfma_f32_16x16x32_bf16 v[52:55], v[56:59], v[170:173], v[52:55]
	v_mfma_f32_16x16x32_bf16 v[56:59], v[60:63], v[166:169], 0
	v_mfma_f32_16x16x32_bf16 v[146:149], v[68:71], v[154:157], v[146:149]
	v_mfma_f32_16x16x32_bf16 v[154:157], v[60:63], v[158:161], 0
	v_mfma_f32_16x16x32_bf16 v[56:59], v[68:71], v[170:173], v[56:59]
	v_mfma_f32_16x16x32_bf16 v[154:157], v[68:71], v[162:165], v[154:157]
	s_barrier
	ds_read_b128 v[60:63], v242
	ds_read_b128 v[68:71], v242 offset:1024
	ds_read_b128 v[158:161], v242 offset:2048
	ds_read_b128 v[162:165], v242 offset:3072
	ds_read_b128 v[166:169], v243
	ds_read_b128 v[170:173], v243 offset:1024
	ds_read_b128 v[198:201], v243 offset:2048
	ds_read_b128 v[202:205], v243 offset:3072
	s_mov_b32 m0, s49
	v_lshl_add_u64 v[64:65], s[12:13], 0, v[18:19]
	ds_read_b128 v[206:209], v133 offset:32768
	ds_read_b128 v[210:213], v133 offset:33792
	ds_read_b128 v[214:217], v133 offset:34816
	ds_read_b128 v[218:221], v133 offset:35840
	ds_read_b128 v[222:225], v133 offset:36864
	ds_read_b128 v[226:229], v133 offset:37888
	ds_read_b128 v[230:233], v133 offset:38912
	ds_read_b128 v[234:237], v133 offset:39936
	global_load_lds_dwordx4 v[64:65], off
	v_lshl_add_u64 v[64:65], s[12:13], 0, v[32:33]
	s_mov_b32 m0, s50
	s_nop 0
	global_load_lds_dwordx4 v[64:65], off
	s_waitcnt vmcnt(8)
	s_waitcnt lgkmcnt(0)
	s_barrier
	s_waitcnt lgkmcnt(0)
	v_mfma_f32_16x16x32_bf16 v[104:107], v[60:63], v[206:209], v[104:107]
	v_mfma_f32_16x16x32_bf16 v[108:111], v[158:161], v[206:209], v[108:111]
	v_mfma_f32_16x16x32_bf16 v[112:115], v[60:63], v[214:217], v[112:115]
	v_mfma_f32_16x16x32_bf16 v[116:119], v[158:161], v[214:217], v[116:119]
	v_mfma_f32_16x16x32_bf16 v[120:123], v[60:63], v[222:225], v[120:123]
	v_mfma_f32_16x16x32_bf16 v[124:127], v[158:161], v[222:225], v[124:127]
	v_mfma_f32_16x16x32_bf16 v[104:107], v[68:71], v[210:213], v[104:107]
	v_mfma_f32_16x16x32_bf16 v[108:111], v[162:165], v[210:213], v[108:111]
	v_mfma_f32_16x16x32_bf16 v[112:115], v[68:71], v[218:221], v[112:115]
	v_mfma_f32_16x16x32_bf16 v[116:119], v[162:165], v[218:221], v[116:119]
	v_mfma_f32_16x16x32_bf16 v[120:123], v[68:71], v[226:229], v[120:123]
	v_mfma_f32_16x16x32_bf16 v[124:127], v[162:165], v[226:229], v[124:127]
	v_mfma_f32_16x16x32_bf16 v[134:137], v[60:63], v[230:233], v[134:137]
	v_mfma_f32_16x16x32_bf16 v[138:141], v[158:161], v[230:233], v[138:141]
	v_mfma_f32_16x16x32_bf16 v[134:137], v[68:71], v[234:237], v[134:137]
	v_mfma_f32_16x16x32_bf16 v[138:141], v[162:165], v[234:237], v[138:141]
	v_mfma_f32_16x16x32_bf16 v[72:75], v[198:201], v[206:209], v[72:75]
	v_mfma_f32_16x16x32_bf16 v[76:79], v[166:169], v[214:217], v[76:79]
	v_mfma_f32_16x16x32_bf16 v[80:83], v[198:201], v[214:217], v[80:83]
	v_mfma_f32_16x16x32_bf16 v[84:87], v[166:169], v[222:225], v[84:87]
	v_mfma_f32_16x16x32_bf16 v[88:91], v[198:201], v[222:225], v[88:91]
	v_mfma_f32_16x16x32_bf16 v[92:95], v[166:169], v[230:233], v[92:95]
	v_mfma_f32_16x16x32_bf16 v[96:99], v[198:201], v[230:233], v[96:99]
	v_mfma_f32_16x16x32_bf16 v[142:145], v[166:169], v[206:209], v[142:145]
	v_mfma_f32_16x16x32_bf16 v[72:75], v[202:205], v[210:213], v[72:75]
	v_mfma_f32_16x16x32_bf16 v[76:79], v[170:173], v[218:221], v[76:79]
	v_mfma_f32_16x16x32_bf16 v[80:83], v[202:205], v[218:221], v[80:83]
	v_mfma_f32_16x16x32_bf16 v[84:87], v[170:173], v[226:229], v[84:87]
	v_mfma_f32_16x16x32_bf16 v[88:91], v[202:205], v[226:229], v[88:91]
	v_mfma_f32_16x16x32_bf16 v[92:95], v[170:173], v[234:237], v[92:95]
	v_mfma_f32_16x16x32_bf16 v[96:99], v[202:205], v[234:237], v[96:99]
	v_mfma_f32_16x16x32_bf16 v[142:145], v[170:173], v[210:213], v[142:145]
	s_barrier
	s_mov_b32 m0, s39
	v_lshl_add_u64 v[64:65], s[36:37], 0, v[66:67]
	ds_read_b128 v[206:209], v133 offset:49152
	ds_read_b128 v[210:213], v133 offset:50176
	ds_read_b128 v[214:217], v133 offset:51200
	ds_read_b128 v[218:221], v133 offset:52224
	ds_read_b128 v[222:225], v133 offset:53248
	ds_read_b128 v[226:229], v133 offset:54272
	ds_read_b128 v[230:233], v133 offset:55296
	ds_read_b128 v[234:237], v133 offset:56320
	global_load_lds_dwordx4 v[64:65], off
	v_lshl_add_u64 v[64:65], s[36:37], 0, v[34:35]
	s_mov_b32 m0, s45
	v_lshl_add_u64 v[34:35], s[20:21], 0, v[34:35]
	global_load_lds_dwordx4 v[64:65], off
	v_lshl_add_u64 v[64:65], s[20:21], 0, v[66:67]
	s_mov_b32 m0, s51
	s_mov_b64 s[10:11], 0x180
	global_load_lds_dwordx4 v[64:65], off
	s_mov_b32 m0, s52
	s_nop 0
	global_load_lds_dwordx4 v[34:35], off
	v_lshl_add_u64 v[34:35], v[22:23], 0, s[10:11]
	s_mov_b32 m0, s44
	s_nop 0
	global_load_lds_dwordx4 v[34:35], off
	v_lshl_add_u64 v[34:35], v[24:25], 0, s[10:11]
	s_mov_b32 m0, s48
	s_nop 0
	global_load_lds_dwordx4 v[34:35], off
	s_waitcnt vmcnt(8)
	s_waitcnt lgkmcnt(0)
	s_barrier
	s_waitcnt lgkmcnt(0)
	v_mfma_f32_16x16x32_bf16 v[64:67], v[60:63], v[206:209], v[174:177]
	v_mfma_f32_16x16x32_bf16 v[34:37], v[60:63], v[230:233], v[36:39]
	v_mfma_f32_16x16x32_bf16 v[38:41], v[158:161], v[230:233], v[40:43]
	v_mfma_f32_16x16x32_bf16 v[64:67], v[68:71], v[210:213], v[64:67]
	v_mfma_f32_16x16x32_bf16 v[174:177], v[158:161], v[206:209], v[178:181]
	v_mfma_f32_16x16x32_bf16 v[178:181], v[60:63], v[214:217], v[182:185]
	v_mfma_f32_16x16x32_bf16 v[182:185], v[158:161], v[214:217], v[186:189]
	v_mfma_f32_16x16x32_bf16 v[186:189], v[60:63], v[222:225], v[190:193]
	v_mfma_f32_16x16x32_bf16 v[190:193], v[158:161], v[222:225], v[194:197]
	v_mfma_f32_16x16x32_bf16 v[34:37], v[68:71], v[234:237], v[34:37]
	v_mfma_f32_16x16x32_bf16 v[38:41], v[162:165], v[234:237], v[38:41]
	v_mfma_f32_16x16x32_bf16 v[174:177], v[162:165], v[210:213], v[174:177]
	v_mfma_f32_16x16x32_bf16 v[178:181], v[68:71], v[218:221], v[178:181]
	v_mfma_f32_16x16x32_bf16 v[182:185], v[162:165], v[218:221], v[182:185]
	v_mfma_f32_16x16x32_bf16 v[186:189], v[68:71], v[226:229], v[186:189]
	v_mfma_f32_16x16x32_bf16 v[190:193], v[162:165], v[226:229], v[190:193]
	v_mfma_f32_16x16x32_bf16 v[42:45], v[166:169], v[206:209], v[44:47]
	v_mfma_f32_16x16x32_bf16 v[46:49], v[198:201], v[206:209], v[48:51]
	v_mfma_f32_16x16x32_bf16 v[60:63], v[166:169], v[214:217], v[100:103]
	v_mfma_f32_16x16x32_bf16 v[68:71], v[198:201], v[214:217], v[146:149]
	v_mfma_f32_16x16x32_bf16 v[100:103], v[166:169], v[222:225], v[150:153]
	v_mfma_f32_16x16x32_bf16 v[50:53], v[166:169], v[230:233], v[52:55]
	v_mfma_f32_16x16x32_bf16 v[54:57], v[198:201], v[230:233], v[56:59]
	v_mfma_f32_16x16x32_bf16 v[42:45], v[170:173], v[210:213], v[42:45]
	v_mfma_f32_16x16x32_bf16 v[46:49], v[202:205], v[210:213], v[46:49]
	v_mfma_f32_16x16x32_bf16 v[60:63], v[170:173], v[218:221], v[60:63]
	v_mfma_f32_16x16x32_bf16 v[68:71], v[202:205], v[218:221], v[68:71]
	v_mfma_f32_16x16x32_bf16 v[100:103], v[170:173], v[226:229], v[100:103]
	v_mfma_f32_16x16x32_bf16 v[146:149], v[198:201], v[222:225], v[154:157]
	v_mfma_f32_16x16x32_bf16 v[50:53], v[170:173], v[234:237], v[50:53]
	v_mfma_f32_16x16x32_bf16 v[54:57], v[202:205], v[234:237], v[54:57]
	v_mfma_f32_16x16x32_bf16 v[146:149], v[202:205], v[226:229], v[146:149]
	s_barrier
	ds_read_b128 v[150:153], v128
	ds_read_b128 v[154:157], v128 offset:1024
	ds_read_b128 v[158:161], v128 offset:2048
	ds_read_b128 v[162:165], v128 offset:3072
	ds_read_b128 v[166:169], v129
	ds_read_b128 v[170:173], v129 offset:1024
	ds_read_b128 v[194:197], v129 offset:2048
	ds_read_b128 v[198:201], v129 offset:3072
	s_mov_b32 m0, s60
	v_lshl_add_u64 v[18:19], s[0:1], 0, v[18:19]
	ds_read_b128 v[202:205], v133
	ds_read_b128 v[206:209], v133 offset:1024
	ds_read_b128 v[210:213], v133 offset:2048
	ds_read_b128 v[214:217], v133 offset:3072
	ds_read_b128 v[218:221], v133 offset:4096
	ds_read_b128 v[222:225], v133 offset:5120
	ds_read_b128 v[226:229], v133 offset:6144
	ds_read_b128 v[230:233], v133 offset:7168
	global_load_lds_dwordx4 v[18:19], off
	v_lshl_add_u64 v[18:19], s[0:1], 0, v[32:33]
	s_mov_b32 m0, s59
	s_nop 0
	global_load_lds_dwordx4 v[18:19], off
	s_waitcnt vmcnt(8)
	s_waitcnt lgkmcnt(0)
	s_barrier
	s_waitcnt lgkmcnt(0)
	v_mfma_f32_16x16x32_bf16 v[112:115], v[150:153], v[210:213], v[112:115]
	v_mfma_f32_16x16x32_bf16 v[234:237], v[154:157], v[214:217], v[112:115]
	v_mfma_f32_16x16x32_bf16 v[112:115], v[158:161], v[210:213], v[116:119]
	v_mfma_f32_16x16x32_bf16 v[238:241], v[162:165], v[214:217], v[112:115]
	v_mfma_f32_16x16x32_bf16 v[112:115], v[150:153], v[218:221], v[120:123]
	v_mfma_f32_16x16x32_bf16 v[118:121], v[154:157], v[222:225], v[112:115]
	v_mfma_f32_16x16x32_bf16 v[112:115], v[158:161], v[218:221], v[124:127]
	v_mfma_f32_16x16x32_bf16 v[104:107], v[150:153], v[202:205], v[104:107]
	v_mfma_f32_16x16x32_bf16 v[108:111], v[158:161], v[202:205], v[108:111]
	v_mfma_f32_16x16x32_bf16 v[126:129], v[162:165], v[222:225], v[112:115]
	v_mfma_f32_16x16x32_bf16 v[112:115], v[150:153], v[226:229], v[134:137]
	v_mfma_f32_16x16x32_bf16 v[104:107], v[154:157], v[206:209], v[104:107]
	v_mfma_f32_16x16x32_bf16 v[108:111], v[162:165], v[206:209], v[108:111]
	v_mfma_f32_16x16x32_bf16 v[134:137], v[154:157], v[230:233], v[112:115]
	v_mfma_f32_16x16x32_bf16 v[112:115], v[158:161], v[226:229], v[138:141]
	v_mfma_f32_16x16x32_bf16 v[138:141], v[162:165], v[230:233], v[112:115]
	v_mfma_f32_16x16x32_bf16 v[80:83], v[194:197], v[210:213], v[80:83]
	v_mfma_f32_16x16x32_bf16 v[112:115], v[166:169], v[202:205], v[142:145]
	v_mfma_f32_16x16x32_bf16 v[72:75], v[194:197], v[202:205], v[72:75]
	v_mfma_f32_16x16x32_bf16 v[202:205], v[198:201], v[214:217], v[80:83]
	v_mfma_f32_16x16x32_bf16 v[80:83], v[166:169], v[218:221], v[84:87]
	v_mfma_f32_16x16x32_bf16 v[142:145], v[170:173], v[206:209], v[112:115]
	v_mfma_f32_16x16x32_bf16 v[72:75], v[198:201], v[206:209], v[72:75]
	v_mfma_f32_16x16x32_bf16 v[206:209], v[170:173], v[222:225], v[80:83]
	v_mfma_f32_16x16x32_bf16 v[80:83], v[194:197], v[218:221], v[88:91]
	v_mfma_f32_16x16x32_bf16 v[76:79], v[166:169], v[210:213], v[76:79]
	v_mfma_f32_16x16x32_bf16 v[86:89], v[198:201], v[222:225], v[80:83]
	v_mfma_f32_16x16x32_bf16 v[80:83], v[166:169], v[226:229], v[92:95]
	v_mfma_f32_16x16x32_bf16 v[76:79], v[170:173], v[214:217], v[76:79]
	v_mfma_f32_16x16x32_bf16 v[210:213], v[170:173], v[230:233], v[80:83]
	v_mfma_f32_16x16x32_bf16 v[80:83], v[194:197], v[226:229], v[96:99]
	v_mfma_f32_16x16x32_bf16 v[214:217], v[198:201], v[230:233], v[80:83]
	s_barrier
	s_mov_b32 m0, s56
	s_nop 3
	ds_read_b128 v[80:83], v133 offset:16384
	ds_read_b128 v[90:93], v133 offset:17408
	ds_read_b128 v[94:97], v133 offset:18432
	ds_read_b128 v[112:115], v133 offset:19456
	ds_read_b128 v[122:125], v133 offset:20480
	ds_read_b128 v[218:221], v133 offset:21504
	ds_read_b128 v[222:225], v133 offset:22528
	ds_read_b128 v[226:229], v133 offset:23552
	global_load_lds_dwordx4 v[28:29], off
	s_mov_b32 m0, s55
	s_nop 0
	global_load_lds_dwordx4 v[30:31], off
	s_mov_b32 m0, s58
	s_nop 0
	global_load_lds_dwordx4 v[26:27], off
	s_mov_b32 m0, s57
	s_nop 0
	global_load_lds_dwordx4 v[20:21], off
	s_mov_b32 m0, s53
	s_nop 0
	global_load_lds_dwordx4 v[22:23], off
	s_mov_b32 m0, s54
	s_nop 0
	global_load_lds_dwordx4 v[24:25], off
	s_waitcnt vmcnt(8)
	s_waitcnt lgkmcnt(0)
	s_barrier
	s_waitcnt lgkmcnt(0)
	v_mfma_f32_16x16x32_bf16 v[18:21], v[150:153], v[80:83], v[64:67]
	v_mfma_f32_16x16x32_bf16 v[22:25], v[158:161], v[80:83], v[174:177]
	v_mfma_f32_16x16x32_bf16 v[26:29], v[150:153], v[94:97], v[178:181]
	v_mfma_f32_16x16x32_bf16 v[30:33], v[158:161], v[94:97], v[182:185]
	v_mfma_f32_16x16x32_bf16 v[64:67], v[150:153], v[122:125], v[186:189]
	v_mfma_f32_16x16x32_bf16 v[34:37], v[150:153], v[222:225], v[34:37]
	v_mfma_f32_16x16x32_bf16 v[18:21], v[154:157], v[90:93], v[18:21]
	v_mfma_f32_16x16x32_bf16 v[22:25], v[162:165], v[90:93], v[22:25]
	v_mfma_f32_16x16x32_bf16 v[26:29], v[154:157], v[112:115], v[26:29]
	v_mfma_f32_16x16x32_bf16 v[30:33], v[162:165], v[112:115], v[30:33]
	v_mfma_f32_16x16x32_bf16 v[174:177], v[154:157], v[218:221], v[64:67]
	v_mfma_f32_16x16x32_bf16 v[64:67], v[158:161], v[122:125], v[190:193]
	v_mfma_f32_16x16x32_bf16 v[34:37], v[154:157], v[226:229], v[34:37]
	v_mfma_f32_16x16x32_bf16 v[38:41], v[158:161], v[222:225], v[38:41]
	v_mfma_f32_16x16x32_bf16 v[178:181], v[162:165], v[218:221], v[64:67]
	v_mfma_f32_16x16x32_bf16 v[150:153], v[162:165], v[226:229], v[38:41]
	v_mfma_f32_16x16x32_bf16 v[38:41], v[166:169], v[80:83], v[42:45]
	v_mfma_f32_16x16x32_bf16 v[42:45], v[170:173], v[90:93], v[38:41]
	v_mfma_f32_16x16x32_bf16 v[38:41], v[194:197], v[80:83], v[46:49]
	v_mfma_f32_16x16x32_bf16 v[154:157], v[198:201], v[90:93], v[38:41]
	v_mfma_f32_16x16x32_bf16 v[38:41], v[166:169], v[94:97], v[60:63]
	v_mfma_f32_16x16x32_bf16 v[158:161], v[170:173], v[112:115], v[38:41]
	v_mfma_f32_16x16x32_bf16 v[38:41], v[194:197], v[94:97], v[68:71]
	v_mfma_f32_16x16x32_bf16 v[162:165], v[198:201], v[112:115], v[38:41]
	v_mfma_f32_16x16x32_bf16 v[38:41], v[166:169], v[122:125], v[100:103]
	v_mfma_f32_16x16x32_bf16 v[182:185], v[170:173], v[218:221], v[38:41]
	v_mfma_f32_16x16x32_bf16 v[38:41], v[194:197], v[122:125], v[146:149]
	v_mfma_f32_16x16x32_bf16 v[146:149], v[198:201], v[218:221], v[38:41]
	v_mfma_f32_16x16x32_bf16 v[38:41], v[166:169], v[222:225], v[50:53]
	v_mfma_f32_16x16x32_bf16 v[166:169], v[170:173], v[226:229], v[38:41]
	v_mfma_f32_16x16x32_bf16 v[38:41], v[194:197], v[222:225], v[54:57]
	v_mfma_f32_16x16x32_bf16 v[170:173], v[198:201], v[226:229], v[38:41]
	s_barrier
	ds_read_b128 v[66:69], v242
	ds_read_b128 v[186:189], v242 offset:1024
	ds_read_b128 v[190:193], v242 offset:2048
	ds_read_b128 v[194:197], v242 offset:3072
	ds_read_b128 v[198:201], v243
	ds_read_b128 v[218:221], v243 offset:1024
	ds_read_b128 v[222:225], v243 offset:2048
	ds_read_b128 v[226:229], v243 offset:3072
	s_mov_b32 m0, s49
	ds_read_b128 v[38:41], v133 offset:32768
	ds_read_b128 v[46:49], v133 offset:33792
	ds_read_b128 v[54:57], v133 offset:34816
	ds_read_b128 v[62:65], v133 offset:35840
	ds_read_b128 v[230:233], v133 offset:36864
	ds_read_b128 v[242:245], v133 offset:37888
	ds_read_b128 v[246:249], v133 offset:38912
	ds_read_b128 v[250:253], v133 offset:39936
	global_load_lds_dwordx4 v[14:15], off
	s_mov_b32 m0, s50
	s_nop 0
	global_load_lds_dwordx4 v[16:17], off
	s_waitcnt vmcnt(8)
	s_waitcnt lgkmcnt(0)
	s_barrier
	s_waitcnt lgkmcnt(0)
	v_mfma_f32_16x16x32_bf16 v[14:17], v[66:69], v[38:41], v[104:107]
	v_mfma_f32_16x16x32_bf16 v[122:125], v[186:189], v[46:49], v[14:17]
	v_mfma_f32_16x16x32_bf16 v[14:17], v[190:193], v[38:41], v[108:111]
	v_mfma_f32_16x16x32_bf16 v[114:117], v[194:197], v[46:49], v[14:17]
	v_mfma_f32_16x16x32_bf16 v[14:17], v[66:69], v[54:57], v[234:237]
	v_mfma_f32_16x16x32_bf16 v[106:109], v[186:189], v[62:65], v[14:17]
	v_mfma_f32_16x16x32_bf16 v[14:17], v[190:193], v[54:57], v[238:241]
	v_mfma_f32_16x16x32_bf16 v[98:101], v[194:197], v[62:65], v[14:17]
	v_mfma_f32_16x16x32_bf16 v[14:17], v[66:69], v[230:233], v[118:121]
	v_mfma_f32_16x16x32_bf16 v[90:93], v[186:189], v[242:245], v[14:17]
	v_mfma_f32_16x16x32_bf16 v[14:17], v[190:193], v[230:233], v[126:129]
	v_mfma_f32_16x16x32_bf16 v[82:85], v[194:197], v[242:245], v[14:17]
	v_mfma_f32_16x16x32_bf16 v[14:17], v[66:69], v[246:249], v[134:137]
	v_mfma_f32_16x16x32_bf16 v[58:61], v[186:189], v[250:253], v[14:17]
	v_mfma_f32_16x16x32_bf16 v[14:17], v[190:193], v[246:249], v[138:141]
	v_mfma_f32_16x16x32_bf16 v[50:53], v[194:197], v[250:253], v[14:17]
	v_mfma_f32_16x16x32_bf16 v[14:17], v[198:201], v[38:41], v[142:145]
	v_mfma_f32_16x16x32_bf16 v[126:129], v[218:221], v[46:49], v[14:17]
	v_mfma_f32_16x16x32_bf16 v[14:17], v[222:225], v[38:41], v[72:75]
	v_mfma_f32_16x16x32_bf16 v[118:121], v[226:229], v[46:49], v[14:17]
	v_mfma_f32_16x16x32_bf16 v[14:17], v[198:201], v[54:57], v[76:79]
	v_mfma_f32_16x16x32_bf16 v[110:113], v[218:221], v[62:65], v[14:17]
	v_mfma_f32_16x16x32_bf16 v[14:17], v[222:225], v[54:57], v[202:205]
	v_mfma_f32_16x16x32_bf16 v[102:105], v[226:229], v[62:65], v[14:17]
	v_mfma_f32_16x16x32_bf16 v[14:17], v[198:201], v[230:233], v[206:209]
	v_mfma_f32_16x16x32_bf16 v[94:97], v[218:221], v[242:245], v[14:17]
	v_mfma_f32_16x16x32_bf16 v[14:17], v[222:225], v[230:233], v[86:89]
	v_mfma_f32_16x16x32_bf16 v[86:89], v[226:229], v[242:245], v[14:17]
	v_mfma_f32_16x16x32_bf16 v[14:17], v[198:201], v[246:249], v[210:213]
	v_mfma_f32_16x16x32_bf16 v[62:65], v[218:221], v[250:253], v[14:17]
	v_mfma_f32_16x16x32_bf16 v[14:17], v[222:225], v[246:249], v[214:217]
	v_mfma_f32_16x16x32_bf16 v[54:57], v[226:229], v[250:253], v[14:17]
	s_barrier
	s_mov_b32 m0, s39
	ds_read_b128 v[134:137], v133 offset:49152
	ds_read_b128 v[138:141], v133 offset:50176
	ds_read_b128 v[142:145], v133 offset:51200
	ds_read_b128 v[202:205], v133 offset:52224
	ds_read_b128 v[206:209], v133 offset:53248
	ds_read_b128 v[210:213], v133 offset:54272
	ds_read_b128 v[214:217], v133 offset:55296
	ds_read_b128 v[230:233], v133 offset:56320
	global_load_lds_dwordx4 v[2:3], off
	s_mov_b32 m0, s45
	s_nop 0
	global_load_lds_dwordx4 v[6:7], off
	s_mov_b32 m0, s51
	s_nop 0
	global_load_lds_dwordx4 v[10:11], off
	s_mov_b32 m0, s52
	s_nop 0
	global_load_lds_dwordx4 v[12:13], off
	s_mov_b32 m0, s44
	s_nop 0
	global_load_lds_dwordx4 v[4:5], off
	s_mov_b32 m0, s48
	s_nop 0
	global_load_lds_dwordx4 v[8:9], off
	s_waitcnt vmcnt(8)
	s_waitcnt lgkmcnt(0)
	s_barrier
	s_waitcnt lgkmcnt(0)
	v_mfma_f32_16x16x32_bf16 v[2:5], v[66:69], v[134:137], v[18:21]
	v_mfma_f32_16x16x32_bf16 v[78:81], v[186:189], v[138:141], v[2:5]
	v_mfma_f32_16x16x32_bf16 v[2:5], v[190:193], v[134:137], v[22:25]
	v_mfma_f32_16x16x32_bf16 v[70:73], v[194:197], v[138:141], v[2:5]
	v_mfma_f32_16x16x32_bf16 v[2:5], v[66:69], v[142:145], v[26:29]
	v_mfma_f32_16x16x32_bf16 v[46:49], v[186:189], v[202:205], v[2:5]
	v_mfma_f32_16x16x32_bf16 v[2:5], v[190:193], v[142:145], v[30:33]
	v_mfma_f32_16x16x32_bf16 v[38:41], v[194:197], v[202:205], v[2:5]
	v_mfma_f32_16x16x32_bf16 v[2:5], v[66:69], v[206:209], v[174:177]
	v_mfma_f32_16x16x32_bf16 v[30:33], v[186:189], v[210:213], v[2:5]
	v_mfma_f32_16x16x32_bf16 v[2:5], v[190:193], v[206:209], v[178:181]
	v_mfma_f32_16x16x32_bf16 v[22:25], v[194:197], v[210:213], v[2:5]
	v_mfma_f32_16x16x32_bf16 v[2:5], v[66:69], v[214:217], v[34:37]
	v_mfma_f32_16x16x32_bf16 v[14:17], v[186:189], v[230:233], v[2:5]
	v_mfma_f32_16x16x32_bf16 v[2:5], v[190:193], v[214:217], v[150:153]
	v_mfma_f32_16x16x32_bf16 v[6:9], v[194:197], v[230:233], v[2:5]
	v_mfma_f32_16x16x32_bf16 v[2:5], v[198:201], v[134:137], v[42:45]
	v_mfma_f32_16x16x32_bf16 v[74:77], v[218:221], v[138:141], v[2:5]
	v_mfma_f32_16x16x32_bf16 v[2:5], v[222:225], v[134:137], v[154:157]
	v_mfma_f32_16x16x32_bf16 v[66:69], v[226:229], v[138:141], v[2:5]
	v_mfma_f32_16x16x32_bf16 v[2:5], v[198:201], v[142:145], v[158:161]
	v_mfma_f32_16x16x32_bf16 v[42:45], v[218:221], v[202:205], v[2:5]
	v_mfma_f32_16x16x32_bf16 v[2:5], v[222:225], v[142:145], v[162:165]
	v_mfma_f32_16x16x32_bf16 v[34:37], v[226:229], v[202:205], v[2:5]
	v_mfma_f32_16x16x32_bf16 v[2:5], v[198:201], v[206:209], v[182:185]
	v_mfma_f32_16x16x32_bf16 v[26:29], v[218:221], v[210:213], v[2:5]
	v_mfma_f32_16x16x32_bf16 v[2:5], v[222:225], v[206:209], v[146:149]
	v_mfma_f32_16x16x32_bf16 v[18:21], v[226:229], v[210:213], v[2:5]
	v_mfma_f32_16x16x32_bf16 v[2:5], v[198:201], v[214:217], v[166:169]
	v_mfma_f32_16x16x32_bf16 v[10:13], v[218:221], v[230:233], v[2:5]
	v_mfma_f32_16x16x32_bf16 v[2:5], v[222:225], v[214:217], v[170:173]
	v_mfma_f32_16x16x32_bf16 v[2:5], v[226:229], v[230:233], v[2:5]
	s_barrier
	s_cbranch_scc1 .LBB0_16
	s_barrier
